# baseline (speedup 1.0000x reference)
; DEVINL int opaque_tid(int wv) { int t = (wv << 6) | (int)__builtin_amdgcn_mbcnt_hi(~0u, __builtin_amdgcn_mbcnt_lo(~0u, 0u)); asm volatile("" : "+v"(t)); return t; }
; DEVINL float shup(float v, int off, int lane) { return __int_as_float(__builtin_amdgcn_ds_bpermute(((lane - off) & 63) << 2, __float_as_int(v))); }
; DEVINL int next_item(int* ctr, char* smem, int wv) {
;   int* slot = (int*)(smem + SMEM_MAIN);
;   __syncthreads();
;   if (opaque_tid(wv) == 0) *slot = atomicAdd(ctr, 1);
;   __syncthreads();
;   return *slot;
; }
; DEVINL void ssd1_item(const Params& p, int layer, int item, char* smem, int wv) {
;     ...
;   const int g = item & 1, c = (item >> 1) & 31, b = item >> 6;
;   const int tok0 = b * SEQ + c * 128;
;   const int LT = wid;
;   u16* Bt = (u16*)smem;
;   u16* Xb = Bt + 128 * 136;
;   float* ac = (float*)(Xb + 4 * 64 * 136);
;   {
;     int hh = wid, hd = g * 8 + hh;
;     float a = -expf(p.a_log[layer * 16 + hd]);
;     float v0 = dtf[(size_t)(tok0 + 2 * lane) * 16 + hd] * a;
;     float v1 = dtf[(size_t)(tok0 + 2 * lane + 1) * 16 + hd] * a;
;     float s = v0 + v1;
; #pragma unroll
;     for (int off = 1; off < 64; off <<= 1) { float tt = shup(s, off, lane); if (lane >= off) s += tt; }
;     float ex = s - (v0 + v1);
;     ac[hh * 128 + 2 * lane] = ex + v0; ac[hh * 128 + 2 * lane + 1] = ex + v0 + v1;
;     acumg[(size_t)(tok0 + 2 * lane) * 16 + hd] = ex + v0;
;     acumg[(size_t)(tok0 + 2 * lane + 1) * 16 + hd] = ex + v0 + v1;
;   }
.LBB0_591:
	s_or_b64 exec, exec, s[0:1]
	s_waitcnt lgkmcnt(0)
	s_barrier
	ds_read_b32 v0, v124
	s_movk_i32 s0, 0xff
	s_waitcnt lgkmcnt(0)
	v_cmp_lt_i32_e32 vcc, s0, v0
	v_readfirstlane_b32 s2, v0
	s_mov_b64 s[0:1], -1
	s_cbranch_vccnz .LBB0_586
	v_mov_b32_e32 v22, v176
	s_and_b32 s28, s2, 1
	v_readfirstlane_b32 s0, v22
	s_bfe_u32 s24, s2, 0x50001
	s_ashr_i32 s25, s2, 6
	s_ashr_i32 s26, s0, 6
	s_lshl_b32 s0, s25, 12
	s_lshl_b32 s1, s24, 7
	s_lshl_b32 s76, s28, 3
	s_or_b32 s27, s1, s0
	s_add_i32 s0, s26, s76
	s_ashr_i32 s1, s0, 31
	v_readlane_b32 s4, v254, 2
	s_lshl_b64 s[2:3], s[0:1], 2
	v_readlane_b32 s16, v254, 14
	v_readlane_b32 s17, v254, 15
	s_add_u32 s2, s16, s2
	s_addc_u32 s3, s17, s3
	global_load_dword v0, v1, s[2:3]
	v_and_b32_e32 v127, 63, v22
	v_lshlrev_b32_e32 v23, 1, v127
	v_or_b32_e32 v2, s27, v23
	v_ashrrev_i32_e32 v3, 31, v2
	v_lshl_add_u64 v[4:5], v[2:3], 4, s[0:1]
	v_or_b32_e32 v2, 1, v2
	v_ashrrev_i32_e32 v3, 31, v2
	v_readlane_b32 s2, v254, 52
	v_lshl_add_u64 v[2:3], v[2:3], 4, s[0:1]
	v_readlane_b32 s3, v254, 53
	v_lshlrev_b64 v[2:3], 2, v[2:3]
	v_lshlrev_b64 v[4:5], 2, v[4:5]
	v_lshl_add_u64 v[8:9], s[2:3], 0, v[2:3]
	v_lshl_add_u64 v[6:7], s[2:3], 0, v[4:5]
	global_load_dword v8, v[8:9], off
	s_nop 0
	global_load_dword v9, v[6:7], off
	s_mov_b32 s0, 0x3fb8aa3b
	s_mov_b32 s1, 0xc2ce8ed0
	s_mov_b32 s2, 0x42b17218
	v_mov_b64_e32 v[18:19], s[90:91]
	v_or_b32_e32 v40, s27, v127
	s_lshl_b32 s16, s26, 4
	s_lshl_b32 s74, s28, 8
	s_ashr_i32 s17, s16, 31
	v_or_b32_e32 v57, 64, v127
	v_and_b32_e32 v56, 15, v22
	v_add_u32_e32 v48, 0, v23
	v_bfe_u32 v47, v22, 4, 2
	v_lshlrev_b32_e32 v44, 3, v47
	v_or_b32_e32 v41, s27, v56
	s_waitcnt vmcnt(10)
	v_lshlrev_b32_e32 v64, 1, v44
	v_readlane_b32 s5, v254, 3
	v_readlane_b32 s6, v254, 4
	v_readlane_b32 s7, v254, 5
	v_readlane_b32 s8, v254, 6
	v_readlane_b32 s9, v254, 7
	v_readlane_b32 s10, v254, 8
	v_readlane_b32 s11, v254, 9
	v_readlane_b32 s12, v254, 10
	v_readlane_b32 s13, v254, 11
	v_readlane_b32 s14, v254, 12
	v_readlane_b32 s15, v254, 13
	v_readlane_b32 s18, v254, 16
	v_readlane_b32 s19, v254, 17
	s_waitcnt vmcnt(2)
	v_mul_f32_e32 v6, 0x3fb8aa3b, v0
	v_fma_f32 v7, v0, s0, -v6
	v_rndne_f32_e32 v10, v6
	v_fmac_f32_e32 v7, 0x32a5705f, v0
	v_sub_f32_e32 v6, v6, v10
	v_add_f32_e32 v6, v6, v7
	v_cvt_i32_f32_e32 v10, v10
	v_exp_f32_e32 v6, v6
	v_cmp_ngt_f32_e32 vcc, s1, v0
	v_lshlrev_b32_e32 v7, 2, v22
	v_add_u32_e32 v11, 0xfc, v7
	v_ldexp_f32 v6, v6, v10
	v_cndmask_b32_e32 v6, 0, v6, vcc
	v_cmp_nlt_f32_e32 vcc, s2, v0
	v_and_b32_e32 v11, 0xfc, v11
	v_add_u32_e32 v10, 0xf8, v7
	v_cndmask_b32_e32 v0, v125, v6, vcc
	s_waitcnt vmcnt(1)
	v_mul_f32_e32 v6, v8, v0
	s_waitcnt vmcnt(0)
	v_fma_f32 v12, v9, -v0, -v6
	ds_bpermute_b32 v6, v11, v12
	v_cmp_eq_u32_e32 vcc, 0, v127
	v_and_b32_e32 v10, 0xfc, v10
	v_add_u32_e32 v11, 0xf0, v7
	v_and_b32_e32 v11, 0xfc, v11
	s_waitcnt lgkmcnt(0)
	v_add_f32_e32 v6, v12, v6
	v_cndmask_b32_e32 v6, v6, v12, vcc
	ds_bpermute_b32 v10, v10, v6
	v_cmp_gt_u32_e32 vcc, 2, v127
	s_movk_i32 s0, 0x80
	v_add_u32_e32 v13, 0xc0, v7
	v_bitop3_b32 v14, v7, s0, v126 bitop3:0x6c
	s_waitcnt lgkmcnt(0)
	v_add_f32_e32 v10, v6, v10
	v_cndmask_b32_e32 v6, v10, v6, vcc
	ds_bpermute_b32 v10, v11, v6
	v_add_u32_e32 v11, 0xe0, v7
	v_cmp_gt_u32_e32 vcc, 4, v127
	v_and_b32_e32 v7, 0xfc, v11
	v_and_b32_e32 v13, 0xfc, v13
	s_waitcnt lgkmcnt(0)
	v_add_f32_e32 v10, v6, v10
	v_cndmask_b32_e32 v10, v10, v6, vcc
	ds_bpermute_b32 v11, v7, v10
	v_cmp_gt_u32_e32 vcc, 8, v127
	v_mad_i64_i32 v[6:7], s[0:1], v40, s29, v[18:19]
	v_readlane_b32 s0, v254, 56
	s_waitcnt lgkmcnt(0)
	v_add_f32_e32 v11, v10, v11
	v_cndmask_b32_e32 v10, v11, v10, vcc
	ds_bpermute_b32 v11, v13, v10
	v_cmp_gt_u32_e32 vcc, 16, v127
	v_readlane_b32 s1, v254, 57
	v_lshl_add_u64 v[6:7], v[6:7], 0, s[74:75]
	s_waitcnt lgkmcnt(0)
	v_add_f32_e32 v11, v10, v11
	v_cndmask_b32_e32 v13, v11, v10, vcc
	ds_bpermute_b32 v14, v14, v13
	v_lshl_add_u64 v[4:5], s[0:1], 0, v[4:5]
	v_lshl_add_u64 v[2:3], s[0:1], 0, v[2:3]
	s_lshl_b64 s[0:1], s[16:17], 1
	v_lshl_add_u64 v[10:11], v[6:7], 0, s[0:1]
	s_waitcnt lgkmcnt(0)
; DEVINL f32x4 mfma16(bf16x8 a, bf16x8 b, f32x4 c) { return __builtin_amdgcn_mfma_f32_16x16x32_bf16(a, b, c, 0, 0, 0); }
; DEVINL float shup(float v, int off, int lane) { return __int_as_float(__builtin_amdgcn_ds_bpermute(((lane - off) & 63) << 2, __float_as_int(v))); }
; DEVINL void ssd1_item(const Params& p, int layer, int item, char* smem, int wv) {
;     ...
;     for (int off = 1; off < 64; off <<= 1) { float tt = shup(s, off, lane); if (lane >= off) s += tt; }
;     float ex = s - (v0 + v1);
;     ac[hh * 128 + 2 * lane] = ex + v0; ac[hh * 128 + 2 * lane + 1] = ex + v0 + v1;
;     acumg[(size_t)(tok0 + 2 * lane) * 16 + hd] = ex + v0;
;     acumg[(size_t)(tok0 + 2 * lane + 1) * 16 + hd] = ex + v0 + v1;
;   }
; #pragma unroll
;   for (int i = 0; i < 4; ++i) {
;     const int combo = wid * 4 + i; const int nc = combo >> 1, s = lane + 64 * (combo & 1);
;     bf16x8 raw = *(const bf16x8*)(xc + (size_t)(tok0 + s) * 1536 + 1024 + g * 128 + nc * 8);
; #pragma unroll
;     for (int k = 0; k < 8; ++k) Bt[(nc * 8 + k) * 136 + s] = (u16)raw[k];
;   }
;   f32x4 G[8];
; #pragma unroll
;   for (int st = 0; st < 8; ++st) G[st] = f32x4{0.f, 0.f, 0.f, 0.f};
; #pragma unroll
;   for (int kc = 0; kc < 4; ++kc) {
;     bf16x8 cf = *(const bf16x8*)(xc + (size_t)(tok0 + LT * 16 + fr) * 1536 + 1280 + g * 128 + kc * 32 + fq * 8);
; #pragma unroll
;     for (int st = 0; st < 8; ++st) {
;       if (st <= LT) {
;         bf16x8 bfm = *(const bf16x8*)(xc + (size_t)(tok0 + st * 16 + fr) * 1536 + 1024 + g * 128 + kc * 32 + fq * 8);
;         G[st] = mfma16(bfm, cf, G[st]);
;       }
;     }
;   }
	v_add_f32_e32 v6, v13, v14
	v_cmp_gt_u32_e32 vcc, 32, v127
	s_lshl_b32 s17, s28, 7
	s_nop 0
	v_cndmask_b32_e32 v6, v6, v13, vcc
	v_sub_f32_e32 v6, v6, v12
	v_fma_f32 v20, v9, -v0, v6
	v_fma_f32 v21, v8, -v0, v20
	v_or_b32_e32 v0, s27, v57
	v_mad_i64_i32 v[6:7], s[2:3], v0, s29, v[18:19]
	v_lshl_add_u64 v[6:7], v[6:7], 0, s[74:75]
	v_lshl_add_u64 v[14:15], v[6:7], 0, s[0:1]
	s_add_i32 s0, s16, s27
	v_or_b32_e32 v24, s0, v56
	v_mad_i64_i32 v[18:19], s[0:1], v24, s29, v[18:19]
	v_and_b32_e32 v0, 48, v22
	v_lshl_add_u64 v[18:19], v[18:19], 0, s[74:75]
	global_store_dword v[4:5], v20, off
	global_store_dword v[2:3], v21, off
	v_lshl_add_u64 v[42:43], v[18:19], 0, v[0:1]
	s_lshl_b32 s98, s17, 1
	s_mov_b32 s99, 0
	v_mov_b32_e32 v208, v64
	v_mov_b32_e32 v209, 0
	v_mov_b32_e32 v204, v41
	v_mov_b64_e32 v[206:207], s[90:91]
	v_mad_i64_i32 v[206:207], s[100:101], v204, s29, v[206:207]
	v_lshl_add_u64 v[206:207], v[206:207], 0, s[98:99]
	v_lshl_add_u64 v[206:207], v[206:207], 0, v[208:209]
	global_load_dwordx4 v[200:203], v[206:207], off offset:2048
	global_load_dwordx4 v[200:203], v[206:207], off offset:2112
	global_load_dwordx4 v[200:203], v[206:207], off offset:2176
	global_load_dwordx4 v[200:203], v[206:207], off offset:2240
	v_or_b32_e32 v204, 16, v41
	v_mov_b64_e32 v[206:207], s[90:91]
	v_mad_i64_i32 v[206:207], s[100:101], v204, s29, v[206:207]
	v_lshl_add_u64 v[206:207], v[206:207], 0, s[98:99]
	v_lshl_add_u64 v[206:207], v[206:207], 0, v[208:209]
	global_load_dwordx4 v[200:203], v[206:207], off offset:2048
	global_load_dwordx4 v[200:203], v[206:207], off offset:2112
	global_load_dwordx4 v[200:203], v[206:207], off offset:2176
	global_load_dwordx4 v[200:203], v[206:207], off offset:2240
	v_or_b32_e32 v204, 32, v41
	v_mov_b64_e32 v[206:207], s[90:91]
	v_mad_i64_i32 v[206:207], s[100:101], v204, s29, v[206:207]
	v_lshl_add_u64 v[206:207], v[206:207], 0, s[98:99]
	v_lshl_add_u64 v[206:207], v[206:207], 0, v[208:209]
	global_load_dwordx4 v[200:203], v[206:207], off offset:2048
	global_load_dwordx4 v[200:203], v[206:207], off offset:2112
	global_load_dwordx4 v[200:203], v[206:207], off offset:2176
	global_load_dwordx4 v[200:203], v[206:207], off offset:2240
	v_or_b32_e32 v204, 48, v41
	v_mov_b64_e32 v[206:207], s[90:91]
	v_mad_i64_i32 v[206:207], s[100:101], v204, s29, v[206:207]
	v_lshl_add_u64 v[206:207], v[206:207], 0, s[98:99]
	v_lshl_add_u64 v[206:207], v[206:207], 0, v[208:209]
	global_load_dwordx4 v[200:203], v[206:207], off offset:2048
	global_load_dwordx4 v[200:203], v[206:207], off offset:2112
	global_load_dwordx4 v[200:203], v[206:207], off offset:2176
	global_load_dwordx4 v[200:203], v[206:207], off offset:2240
	v_or_b32_e32 v204, 64, v41
	v_mov_b64_e32 v[206:207], s[90:91]
	v_mad_i64_i32 v[206:207], s[100:101], v204, s29, v[206:207]
	v_lshl_add_u64 v[206:207], v[206:207], 0, s[98:99]
	v_lshl_add_u64 v[206:207], v[206:207], 0, v[208:209]
	global_load_dwordx4 v[200:203], v[206:207], off offset:2048
	global_load_dwordx4 v[200:203], v[206:207], off offset:2112
	global_load_dwordx4 v[200:203], v[206:207], off offset:2176
	global_load_dwordx4 v[200:203], v[206:207], off offset:2240
	v_or_b32_e32 v204, 80, v41
	v_mov_b64_e32 v[206:207], s[90:91]
	v_mad_i64_i32 v[206:207], s[100:101], v204, s29, v[206:207]
	v_lshl_add_u64 v[206:207], v[206:207], 0, s[98:99]
	v_lshl_add_u64 v[206:207], v[206:207], 0, v[208:209]
	global_load_dwordx4 v[200:203], v[206:207], off offset:2048
	global_load_dwordx4 v[200:203], v[206:207], off offset:2112
	global_load_dwordx4 v[200:203], v[206:207], off offset:2176
	global_load_dwordx4 v[200:203], v[206:207], off offset:2240
	v_or_b32_e32 v204, 96, v41
	v_mov_b64_e32 v[206:207], s[90:91]
	v_mad_i64_i32 v[206:207], s[100:101], v204, s29, v[206:207]
	v_lshl_add_u64 v[206:207], v[206:207], 0, s[98:99]
	v_lshl_add_u64 v[206:207], v[206:207], 0, v[208:209]
	global_load_dwordx4 v[200:203], v[206:207], off offset:2048
	global_load_dwordx4 v[200:203], v[206:207], off offset:2112
	global_load_dwordx4 v[200:203], v[206:207], off offset:2176
	global_load_dwordx4 v[200:203], v[206:207], off offset:2240
	v_or_b32_e32 v204, 112, v41
	v_mov_b64_e32 v[206:207], s[90:91]
	v_mad_i64_i32 v[206:207], s[100:101], v204, s29, v[206:207]
	v_lshl_add_u64 v[206:207], v[206:207], 0, s[98:99]
	v_lshl_add_u64 v[206:207], v[206:207], 0, v[208:209]
	global_load_dwordx4 v[200:203], v[206:207], off offset:2048
	global_load_dwordx4 v[200:203], v[206:207], off offset:2112
	global_load_dwordx4 v[200:203], v[206:207], off offset:2176
	global_load_dwordx4 v[200:203], v[206:207], off offset:2240
	global_load_dwordx4 v[200:203], v[42:43], off offset:2624
	global_load_dwordx4 v[200:203], v[42:43], off offset:2688
	global_load_dwordx4 v[200:203], v[42:43], off offset:2752
	global_load_dwordx4 v[2:5], v[10:11], off offset:2048
	global_load_dwordx4 v[6:9], v[14:15], off offset:2048
	s_nop 0
	global_load_dwordx4 v[10:13], v[10:11], off offset:2064
	s_nop 0
	global_load_dwordx4 v[14:17], v[14:15], off offset:2064
	s_mul_i32 s0, s26, 0x1100
	global_load_dwordx4 v[32:35], v[42:43], off offset:2560
	v_add_u32_e32 v0, s0, v48
	s_lshl_b32 s0, s26, 9
	s_add_i32 s0, s0, 0
	s_or_b32 s1, s16, 8
	v_lshl_add_u32 v18, v127, 3, s0
	s_cmp_gt_i32 s26, -1
	s_mulk_i32 s1, 0x110
	v_add_u32_e32 v18, 0x19800, v18
	s_cselect_b64 s[2:3], -1, 0
	s_cmp_lt_i32 s26, 0
	v_add_u32_e32 v19, s1, v48
	ds_write_b64 v18, v[20:21]
	s_waitcnt vmcnt(4)
	ds_write_b16 v0, v2
	ds_write_b16_d16_hi v0, v2 offset:272
	ds_write_b16 v0, v3 offset:544
	ds_write_b16_d16_hi v0, v3 offset:816
	ds_write_b16 v0, v4 offset:1088
	ds_write_b16_d16_hi v0, v4 offset:1360
	ds_write_b16 v0, v5 offset:1632
	ds_write_b16_d16_hi v0, v5 offset:1904
	s_waitcnt vmcnt(3)
	ds_write_b16 v0, v6 offset:128
	ds_write_b16_d16_hi v0, v6 offset:400
	ds_write_b16 v0, v7 offset:672
	ds_write_b16_d16_hi v0, v7 offset:944
	ds_write_b16 v0, v8 offset:1216
	ds_write_b16_d16_hi v0, v8 offset:1488
	ds_write_b16 v0, v9 offset:1760
	ds_write_b16_d16_hi v0, v9 offset:2032
	s_waitcnt vmcnt(2)
	ds_write_b16 v19, v10
	ds_write_b16_d16_hi v0, v10 offset:2448
	ds_write_b16 v0, v11 offset:2720
	ds_write_b16_d16_hi v0, v11 offset:2992
	ds_write_b16 v0, v12 offset:3264
	ds_write_b16_d16_hi v0, v12 offset:3536
	ds_write_b16 v0, v13 offset:3808
	ds_write_b16_d16_hi v0, v13 offset:4080
	s_waitcnt vmcnt(1)
	ds_write_b16 v19, v14 offset:128
	ds_write_b16_d16_hi v0, v14 offset:2576
	ds_write_b16 v0, v15 offset:2848
	ds_write_b16_d16_hi v0, v15 offset:3120
	ds_write_b16 v0, v16 offset:3392
	ds_write_b16_d16_hi v0, v16 offset:3664
	ds_write_b16 v0, v17 offset:3936
	ds_write_b16_d16_hi v0, v17 offset:4208
	s_cbranch_scc1 .LBB0_594
	v_mov_b64_e32 v[2:3], s[90:91]
	v_mad_i64_i32 v[2:3], s[0:1], v41, s29, v[2:3]
	s_lshl_b32 s74, s17, 1
	v_lshl_add_u64 v[2:3], v[2:3], 0, s[74:75]
	v_mov_b32_e32 v65, v1
	v_lshl_add_u64 v[2:3], v[2:3], 0, v[64:65]
	global_load_dwordx4 v[2:5], v[2:3], off offset:2048
	s_waitcnt vmcnt(0)
	v_mfma_f32_16x16x32_bf16 v[4:7], v[2:5], v[32:35], 0
	s_branch .LBB0_595

; DEVINL int opaque_tid(int wv) { int t = (wv << 6) | (int)__builtin_amdgcn_mbcnt_hi(~0u, __builtin_amdgcn_mbcnt_lo(~0u, 0u)); asm volatile("" : "+v"(t)); return t; }
; DEVINL float shup(float v, int off, int lane) { return __int_as_float(__builtin_amdgcn_ds_bpermute(((lane - off) & 63) << 2, __float_as_int(v))); }
; DEVINL int next_item(int* ctr, char* smem, int wv) {
;   int* slot = (int*)(smem + SMEM_MAIN);
;   __syncthreads();
;   if (opaque_tid(wv) == 0) *slot = atomicAdd(ctr, 1);
;   __syncthreads();
;   return *slot;
; }
; DEVINL void ssd1_item(const Params& p, int layer, int item, char* smem, int wv) {
;     ...
;   const int g = item & 1, c = (item >> 1) & 31, b = item >> 6;
;   const int tok0 = b * SEQ + c * 128;
;   const int LT = wid;
;   u16* Bt = (u16*)smem;
;   u16* Xb = Bt + 128 * 136;
;   float* ac = (float*)(Xb + 4 * 64 * 136);
;   {
;     int hh = wid, hd = g * 8 + hh;
;     float a = -expf(p.a_log[layer * 16 + hd]);
;     float v0 = dtf[(size_t)(tok0 + 2 * lane) * 16 + hd] * a;
;     float v1 = dtf[(size_t)(tok0 + 2 * lane + 1) * 16 + hd] * a;
;     float s = v0 + v1;
; #pragma unroll
;     for (int off = 1; off < 64; off <<= 1) { float tt = shup(s, off, lane); if (lane >= off) s += tt; }
;     float ex = s - (v0 + v1);
;     ac[hh * 128 + 2 * lane] = ex + v0; ac[hh * 128 + 2 * lane + 1] = ex + v0 + v1;
;     acumg[(size_t)(tok0 + 2 * lane) * 16 + hd] = ex + v0;
;     acumg[(size_t)(tok0 + 2 * lane + 1) * 16 + hd] = ex + v0 + v1;
;   }
.LBB0_1613:
	s_or_b64 exec, exec, s[2:3]
	s_waitcnt lgkmcnt(0)
	s_barrier
	ds_read_b32 v0, v124
	s_movk_i32 s0, 0xff
	s_mov_b64 s[2:3], -1
	s_waitcnt lgkmcnt(0)
	v_cmp_lt_i32_e32 vcc, s0, v0
	v_readfirstlane_b32 s1, v0
	s_cbranch_vccnz .LBB0_1608
	v_mov_b32_e32 v22, v176
	s_and_b32 s28, s1, 1
	v_readfirstlane_b32 s0, v22
	s_ashr_i32 s26, s0, 6
	s_bfe_u32 s0, s1, 0x50001
	s_ashr_i32 s1, s1, 6
	s_lshl_b32 s2, s1, 12
	s_lshl_b32 s3, s0, 7
	s_lshl_b32 s88, s28, 3
	s_or_b32 s27, s3, s2
	s_add_i32 s2, s26, s88
	v_readlane_b32 s8, v254, 2
	s_ashr_i32 s3, s2, 31
	v_readlane_b32 s12, v254, 6
	v_readlane_b32 s13, v254, 7
	v_readlane_b32 s14, v254, 8
	v_readlane_b32 s15, v254, 9
	v_readlane_b32 s20, v254, 14
	v_readlane_b32 s21, v254, 15
	s_lshl_b64 s[4:5], s[2:3], 2
	v_readlane_b32 s22, v254, 16
	v_readlane_b32 s23, v254, 17
	s_mov_b64 s[12:13], s[20:21]
	s_add_u32 s4, s12, s4
	s_addc_u32 s5, s13, s5
	global_load_dword v0, v1, s[4:5] offset:64
	v_and_b32_e32 v127, 63, v22
	v_lshlrev_b32_e32 v23, 1, v127
	v_or_b32_e32 v2, s27, v23
	v_ashrrev_i32_e32 v3, 31, v2
	v_lshl_add_u64 v[4:5], v[2:3], 4, s[2:3]
	v_or_b32_e32 v2, 1, v2
	v_ashrrev_i32_e32 v3, 31, v2
	v_readlane_b32 s4, v254, 52
	v_lshl_add_u64 v[2:3], v[2:3], 4, s[2:3]
	v_readlane_b32 s5, v254, 53
	v_lshlrev_b64 v[2:3], 2, v[2:3]
	v_lshlrev_b64 v[4:5], 2, v[4:5]
	v_lshl_add_u64 v[8:9], s[4:5], 0, v[2:3]
	v_lshl_add_u64 v[6:7], s[4:5], 0, v[4:5]
	global_load_dword v8, v[8:9], off
	s_nop 0
	global_load_dword v9, v[6:7], off
	s_mov_b32 s2, 0x3fb8aa3b
	s_mov_b32 s3, 0xc2ce8ed0
	s_mov_b32 s4, 0x42b17218
	v_mov_b64_e32 v[18:19], s[90:91]
	v_or_b32_e32 v40, s27, v127
	v_readlane_b32 s18, v254, 12
	v_readlane_b32 s19, v254, 13
	s_lshl_b32 s18, s26, 4
	s_lshl_b32 s80, s28, 8
	s_ashr_i32 s19, s18, 31
	v_or_b32_e32 v57, 64, v127
	v_and_b32_e32 v56, 15, v22
	v_add_u32_e32 v48, 0, v23
	v_bfe_u32 v47, v22, 4, 2
	v_lshlrev_b32_e32 v44, 3, v47
	v_or_b32_e32 v41, s27, v56
	s_waitcnt vmcnt(10)
	v_lshlrev_b32_e32 v64, 1, v44
	v_readlane_b32 s9, v254, 3
	v_readlane_b32 s10, v254, 4
	v_readlane_b32 s11, v254, 5
	v_readlane_b32 s16, v254, 10
	v_readlane_b32 s17, v254, 11
	s_mov_b64 s[14:15], s[22:23]
	s_waitcnt vmcnt(2)
	v_mul_f32_e32 v6, 0x3fb8aa3b, v0
	v_fma_f32 v7, v0, s2, -v6
	v_rndne_f32_e32 v10, v6
	v_fmac_f32_e32 v7, 0x32a5705f, v0
	v_sub_f32_e32 v6, v6, v10
	v_add_f32_e32 v6, v6, v7
	v_cvt_i32_f32_e32 v10, v10
	v_exp_f32_e32 v6, v6
	v_cmp_ngt_f32_e32 vcc, s3, v0
	v_lshlrev_b32_e32 v7, 2, v22
	v_add_u32_e32 v11, 0xfc, v7
	v_ldexp_f32 v6, v6, v10
	v_cndmask_b32_e32 v6, 0, v6, vcc
	v_cmp_nlt_f32_e32 vcc, s4, v0
	v_and_b32_e32 v11, 0xfc, v11
	v_add_u32_e32 v10, 0xf8, v7
	v_cndmask_b32_e32 v0, v125, v6, vcc
	s_waitcnt vmcnt(1)
	v_mul_f32_e32 v6, v8, v0
	s_waitcnt vmcnt(0)
	v_fma_f32 v12, v9, -v0, -v6
	ds_bpermute_b32 v6, v11, v12
	v_cmp_eq_u32_e32 vcc, 0, v127
	v_and_b32_e32 v10, 0xfc, v10
	v_add_u32_e32 v11, 0xf0, v7
	v_and_b32_e32 v11, 0xfc, v11
	s_waitcnt lgkmcnt(0)
	v_add_f32_e32 v6, v12, v6
	v_cndmask_b32_e32 v6, v6, v12, vcc
	ds_bpermute_b32 v10, v10, v6
	v_cmp_gt_u32_e32 vcc, 2, v127
	s_movk_i32 s2, 0x80
	v_add_u32_e32 v13, 0xc0, v7
	v_bitop3_b32 v14, v7, s2, v126 bitop3:0x6c
	s_waitcnt lgkmcnt(0)
	v_add_f32_e32 v10, v6, v10
	v_cndmask_b32_e32 v6, v10, v6, vcc
	ds_bpermute_b32 v10, v11, v6
	v_add_u32_e32 v11, 0xe0, v7
	v_cmp_gt_u32_e32 vcc, 4, v127
	v_and_b32_e32 v7, 0xfc, v11
	v_and_b32_e32 v13, 0xfc, v13
	s_waitcnt lgkmcnt(0)
	v_add_f32_e32 v10, v6, v10
	v_cndmask_b32_e32 v10, v10, v6, vcc
	ds_bpermute_b32 v11, v7, v10
	v_cmp_gt_u32_e32 vcc, 8, v127
	v_mad_i64_i32 v[6:7], s[2:3], v40, s29, v[18:19]
	v_readlane_b32 s2, v254, 56
	s_waitcnt lgkmcnt(0)
	v_add_f32_e32 v11, v10, v11
	v_cndmask_b32_e32 v10, v11, v10, vcc
	ds_bpermute_b32 v11, v13, v10
	v_cmp_gt_u32_e32 vcc, 16, v127
	v_readlane_b32 s3, v254, 57
	v_lshl_add_u64 v[6:7], v[6:7], 0, s[80:81]
	s_waitcnt lgkmcnt(0)
	v_add_f32_e32 v11, v10, v11
	v_cndmask_b32_e32 v13, v11, v10, vcc
	ds_bpermute_b32 v14, v14, v13
	v_lshl_add_u64 v[4:5], s[2:3], 0, v[4:5]
	v_lshl_add_u64 v[2:3], s[2:3], 0, v[2:3]
	s_lshl_b64 s[2:3], s[18:19], 1
	v_lshl_add_u64 v[10:11], v[6:7], 0, s[2:3]
	s_waitcnt lgkmcnt(0)
; DEVINL f32x4 mfma16(bf16x8 a, bf16x8 b, f32x4 c) { return __builtin_amdgcn_mfma_f32_16x16x32_bf16(a, b, c, 0, 0, 0); }
; DEVINL float shup(float v, int off, int lane) { return __int_as_float(__builtin_amdgcn_ds_bpermute(((lane - off) & 63) << 2, __float_as_int(v))); }
; DEVINL void ssd1_item(const Params& p, int layer, int item, char* smem, int wv) {
;     ...
;     for (int off = 1; off < 64; off <<= 1) { float tt = shup(s, off, lane); if (lane >= off) s += tt; }
;     float ex = s - (v0 + v1);
;     ac[hh * 128 + 2 * lane] = ex + v0; ac[hh * 128 + 2 * lane + 1] = ex + v0 + v1;
;     acumg[(size_t)(tok0 + 2 * lane) * 16 + hd] = ex + v0;
;     acumg[(size_t)(tok0 + 2 * lane + 1) * 16 + hd] = ex + v0 + v1;
;   }
; #pragma unroll
;   for (int i = 0; i < 4; ++i) {
;     const int combo = wid * 4 + i; const int nc = combo >> 1, s = lane + 64 * (combo & 1);
;     bf16x8 raw = *(const bf16x8*)(xc + (size_t)(tok0 + s) * 1536 + 1024 + g * 128 + nc * 8);
; #pragma unroll
;     for (int k = 0; k < 8; ++k) Bt[(nc * 8 + k) * 136 + s] = (u16)raw[k];
;   }
;   f32x4 G[8];
; #pragma unroll
;   for (int st = 0; st < 8; ++st) G[st] = f32x4{0.f, 0.f, 0.f, 0.f};
; #pragma unroll
;   for (int kc = 0; kc < 4; ++kc) {
;     bf16x8 cf = *(const bf16x8*)(xc + (size_t)(tok0 + LT * 16 + fr) * 1536 + 1280 + g * 128 + kc * 32 + fq * 8);
; #pragma unroll
;     for (int st = 0; st < 8; ++st) {
;       if (st <= LT) {
;         bf16x8 bfm = *(const bf16x8*)(xc + (size_t)(tok0 + st * 16 + fr) * 1536 + 1024 + g * 128 + kc * 32 + fq * 8);
;         G[st] = mfma16(bfm, cf, G[st]);
	v_add_f32_e32 v6, v13, v14
	v_cmp_gt_u32_e32 vcc, 32, v127
	s_lshl_b32 s19, s28, 7
	s_nop 0
	v_cndmask_b32_e32 v6, v6, v13, vcc
	v_sub_f32_e32 v6, v6, v12
	v_fma_f32 v20, v9, -v0, v6
	v_fma_f32 v21, v8, -v0, v20
	v_or_b32_e32 v0, s27, v57
	v_mad_i64_i32 v[6:7], s[4:5], v0, s29, v[18:19]
	v_lshl_add_u64 v[6:7], v[6:7], 0, s[80:81]
	v_lshl_add_u64 v[14:15], v[6:7], 0, s[2:3]
	s_add_i32 s2, s18, s27
	v_or_b32_e32 v24, s2, v56
	v_mad_i64_i32 v[18:19], s[2:3], v24, s29, v[18:19]
	v_and_b32_e32 v0, 48, v22
	v_lshl_add_u64 v[18:19], v[18:19], 0, s[80:81]
	global_store_dword v[4:5], v20, off
	global_store_dword v[2:3], v21, off
	v_lshl_add_u64 v[42:43], v[18:19], 0, v[0:1]
	s_lshl_b32 s98, s19, 1
	s_mov_b32 s99, 0
	v_mov_b32_e32 v208, v64
	v_mov_b32_e32 v209, 0
	v_mov_b32_e32 v204, v41
	v_mov_b64_e32 v[206:207], s[90:91]
	v_mad_i64_i32 v[206:207], s[100:101], v204, s29, v[206:207]
	v_lshl_add_u64 v[206:207], v[206:207], 0, s[98:99]
	v_lshl_add_u64 v[206:207], v[206:207], 0, v[208:209]
	global_load_dwordx4 v[200:203], v[206:207], off offset:2048
	global_load_dwordx4 v[200:203], v[206:207], off offset:2112
	global_load_dwordx4 v[200:203], v[206:207], off offset:2176
	global_load_dwordx4 v[200:203], v[206:207], off offset:2240
	v_or_b32_e32 v204, 16, v41
	v_mov_b64_e32 v[206:207], s[90:91]
	v_mad_i64_i32 v[206:207], s[100:101], v204, s29, v[206:207]
	v_lshl_add_u64 v[206:207], v[206:207], 0, s[98:99]
	v_lshl_add_u64 v[206:207], v[206:207], 0, v[208:209]
	global_load_dwordx4 v[200:203], v[206:207], off offset:2048
	global_load_dwordx4 v[200:203], v[206:207], off offset:2112
	global_load_dwordx4 v[200:203], v[206:207], off offset:2176
	global_load_dwordx4 v[200:203], v[206:207], off offset:2240
	v_or_b32_e32 v204, 32, v41
	v_mov_b64_e32 v[206:207], s[90:91]
	v_mad_i64_i32 v[206:207], s[100:101], v204, s29, v[206:207]
	v_lshl_add_u64 v[206:207], v[206:207], 0, s[98:99]
	v_lshl_add_u64 v[206:207], v[206:207], 0, v[208:209]
	global_load_dwordx4 v[200:203], v[206:207], off offset:2048
	global_load_dwordx4 v[200:203], v[206:207], off offset:2112
	global_load_dwordx4 v[200:203], v[206:207], off offset:2176
	global_load_dwordx4 v[200:203], v[206:207], off offset:2240
	v_or_b32_e32 v204, 48, v41
	v_mov_b64_e32 v[206:207], s[90:91]
	v_mad_i64_i32 v[206:207], s[100:101], v204, s29, v[206:207]
	v_lshl_add_u64 v[206:207], v[206:207], 0, s[98:99]
	v_lshl_add_u64 v[206:207], v[206:207], 0, v[208:209]
	global_load_dwordx4 v[200:203], v[206:207], off offset:2048
	global_load_dwordx4 v[200:203], v[206:207], off offset:2112
	global_load_dwordx4 v[200:203], v[206:207], off offset:2176
	global_load_dwordx4 v[200:203], v[206:207], off offset:2240
	v_or_b32_e32 v204, 64, v41
	v_mov_b64_e32 v[206:207], s[90:91]
	v_mad_i64_i32 v[206:207], s[100:101], v204, s29, v[206:207]
	v_lshl_add_u64 v[206:207], v[206:207], 0, s[98:99]
	v_lshl_add_u64 v[206:207], v[206:207], 0, v[208:209]
	global_load_dwordx4 v[200:203], v[206:207], off offset:2048
	global_load_dwordx4 v[200:203], v[206:207], off offset:2112
	global_load_dwordx4 v[200:203], v[206:207], off offset:2176
	global_load_dwordx4 v[200:203], v[206:207], off offset:2240
	v_or_b32_e32 v204, 80, v41
	v_mov_b64_e32 v[206:207], s[90:91]
	v_mad_i64_i32 v[206:207], s[100:101], v204, s29, v[206:207]
	v_lshl_add_u64 v[206:207], v[206:207], 0, s[98:99]
	v_lshl_add_u64 v[206:207], v[206:207], 0, v[208:209]
	global_load_dwordx4 v[200:203], v[206:207], off offset:2048
	global_load_dwordx4 v[200:203], v[206:207], off offset:2112
	global_load_dwordx4 v[200:203], v[206:207], off offset:2176
	global_load_dwordx4 v[200:203], v[206:207], off offset:2240
	v_or_b32_e32 v204, 96, v41
	v_mov_b64_e32 v[206:207], s[90:91]
	v_mad_i64_i32 v[206:207], s[100:101], v204, s29, v[206:207]
	v_lshl_add_u64 v[206:207], v[206:207], 0, s[98:99]
	v_lshl_add_u64 v[206:207], v[206:207], 0, v[208:209]
	global_load_dwordx4 v[200:203], v[206:207], off offset:2048
	global_load_dwordx4 v[200:203], v[206:207], off offset:2112
	global_load_dwordx4 v[200:203], v[206:207], off offset:2176
	global_load_dwordx4 v[200:203], v[206:207], off offset:2240
	v_or_b32_e32 v204, 112, v41
	v_mov_b64_e32 v[206:207], s[90:91]
	v_mad_i64_i32 v[206:207], s[100:101], v204, s29, v[206:207]
	v_lshl_add_u64 v[206:207], v[206:207], 0, s[98:99]
	v_lshl_add_u64 v[206:207], v[206:207], 0, v[208:209]
	global_load_dwordx4 v[200:203], v[206:207], off offset:2048
	global_load_dwordx4 v[200:203], v[206:207], off offset:2112
	global_load_dwordx4 v[200:203], v[206:207], off offset:2176
	global_load_dwordx4 v[200:203], v[206:207], off offset:2240
	global_load_dwordx4 v[200:203], v[42:43], off offset:2624
	global_load_dwordx4 v[200:203], v[42:43], off offset:2688
	global_load_dwordx4 v[200:203], v[42:43], off offset:2752
	global_load_dwordx4 v[2:5], v[10:11], off offset:2048
	global_load_dwordx4 v[6:9], v[14:15], off offset:2048
	s_nop 0
	global_load_dwordx4 v[10:13], v[10:11], off offset:2064
	s_nop 0
	global_load_dwordx4 v[14:17], v[14:15], off offset:2064
	s_mul_i32 s2, s26, 0x1100
	global_load_dwordx4 v[32:35], v[42:43], off offset:2560
	v_add_u32_e32 v0, s2, v48
	s_lshl_b32 s2, s26, 9
	s_add_i32 s2, s2, 0
	s_or_b32 s3, s18, 8
	v_lshl_add_u32 v18, v127, 3, s2
	s_cmp_gt_i32 s26, -1
	s_mulk_i32 s3, 0x110
	v_add_u32_e32 v18, 0x19800, v18
	s_cselect_b64 s[4:5], -1, 0
	s_cmp_lt_i32 s26, 0
	v_add_u32_e32 v19, s3, v48
	ds_write_b64 v18, v[20:21]
	s_waitcnt vmcnt(4)
	ds_write_b16 v0, v2
	ds_write_b16_d16_hi v0, v2 offset:272
	ds_write_b16 v0, v3 offset:544
	ds_write_b16_d16_hi v0, v3 offset:816
	ds_write_b16 v0, v4 offset:1088
	ds_write_b16_d16_hi v0, v4 offset:1360
	ds_write_b16 v0, v5 offset:1632
	ds_write_b16_d16_hi v0, v5 offset:1904
	s_waitcnt vmcnt(3)
	ds_write_b16 v0, v6 offset:128
	ds_write_b16_d16_hi v0, v6 offset:400
	ds_write_b16 v0, v7 offset:672
	ds_write_b16_d16_hi v0, v7 offset:944
	ds_write_b16 v0, v8 offset:1216
	ds_write_b16_d16_hi v0, v8 offset:1488
	ds_write_b16 v0, v9 offset:1760
	ds_write_b16_d16_hi v0, v9 offset:2032
	s_waitcnt vmcnt(2)
	ds_write_b16 v19, v10
	ds_write_b16_d16_hi v0, v10 offset:2448
	ds_write_b16 v0, v11 offset:2720
	ds_write_b16_d16_hi v0, v11 offset:2992
	ds_write_b16 v0, v12 offset:3264
	ds_write_b16_d16_hi v0, v12 offset:3536
	ds_write_b16 v0, v13 offset:3808
	ds_write_b16_d16_hi v0, v13 offset:4080
	s_waitcnt vmcnt(1)
	ds_write_b16 v19, v14 offset:128
	ds_write_b16_d16_hi v0, v14 offset:2576
	ds_write_b16 v0, v15 offset:2848
	ds_write_b16_d16_hi v0, v15 offset:3120
	ds_write_b16 v0, v16 offset:3392
	ds_write_b16_d16_hi v0, v16 offset:3664
	ds_write_b16 v0, v17 offset:3936
	ds_write_b16_d16_hi v0, v17 offset:4208
	s_cbranch_scc1 .LBB0_1616
	v_mov_b64_e32 v[2:3], s[90:91]
	v_mad_i64_i32 v[2:3], s[2:3], v41, s29, v[2:3]
	s_lshl_b32 s80, s19, 1
	v_lshl_add_u64 v[2:3], v[2:3], 0, s[80:81]
	v_mov_b32_e32 v65, v1
	v_lshl_add_u64 v[2:3], v[2:3], 0, v[64:65]
	global_load_dwordx4 v[2:5], v[2:3], off offset:2048
	s_waitcnt vmcnt(0)
	v_mfma_f32_16x16x32_bf16 v[4:7], v[2:5], v[32:35], 0
	s_branch .LBB0_1617

; __global__ void __launch_bounds__(512) hybrid_fwd(Params p) {
;   extern __shared__ __attribute__((aligned(16))) char smem[];
	.amdhsa_kernel _Z10hybrid_fwd6Params
		.amdhsa_group_segment_fixed_size 0
		.amdhsa_private_segment_fixed_size 0
		.amdhsa_kernarg_size 400
		.amdhsa_user_sgpr_count 2
		.amdhsa_user_sgpr_dispatch_ptr 0
		.amdhsa_user_sgpr_queue_ptr 0
		.amdhsa_user_sgpr_kernarg_segment_ptr 1
		.amdhsa_user_sgpr_dispatch_id 0
		.amdhsa_user_sgpr_kernarg_preload_length 0
		.amdhsa_user_sgpr_kernarg_preload_offset 0
		.amdhsa_user_sgpr_private_segment_size 0
		.amdhsa_uses_dynamic_stack 0
		.amdhsa_enable_private_segment 0
		.amdhsa_system_sgpr_workgroup_id_x 1
		.amdhsa_system_sgpr_workgroup_id_y 0
		.amdhsa_system_sgpr_workgroup_id_z 0
		.amdhsa_system_sgpr_workgroup_info 0
		.amdhsa_system_vgpr_workitem_id 0
		.amdhsa_next_free_vgpr 256
		.amdhsa_next_free_sgpr 102
		.amdhsa_accum_offset 256
		.amdhsa_reserve_vcc 1
		.amdhsa_float_round_mode_32 0
		.amdhsa_float_round_mode_16_64 0
		.amdhsa_float_denorm_mode_32 3
		.amdhsa_float_denorm_mode_16_64 3
		.amdhsa_dx10_clamp 1
		.amdhsa_ieee_mode 1
		.amdhsa_fp16_overflow 0
		.amdhsa_tg_split 0
		.amdhsa_exception_fp_ieee_invalid_op 0
		.amdhsa_exception_fp_denorm_src 0
		.amdhsa_exception_fp_ieee_div_zero 0
		.amdhsa_exception_fp_ieee_overflow 0
		.amdhsa_exception_fp_ieee_underflow 0
		.amdhsa_exception_fp_ieee_inexact 0
		.amdhsa_exception_int_div_zero 0
	.end_amdhsa_kernel

; __global__ void __launch_bounds__(512) hybrid_fwd(Params p) {
;   extern __shared__ __attribute__((aligned(16))) char smem[];
amdhsa.kernels:
  - .agpr_count:     0
    .args:
      - .offset:         0
        .size:           144
        .value_kind:     by_value
      - .offset:         144
        .size:           4
        .value_kind:     hidden_block_count_x
      - .offset:         148
        .size:           4
        .value_kind:     hidden_block_count_y
      - .offset:         152
        .size:           4
        .value_kind:     hidden_block_count_z
      - .offset:         156
        .size:           2
        .value_kind:     hidden_group_size_x
      - .offset:         158
        .size:           2
        .value_kind:     hidden_group_size_y
      - .offset:         160
        .size:           2
        .value_kind:     hidden_group_size_z
      - .offset:         162
        .size:           2
        .value_kind:     hidden_remainder_x
      - .offset:         164
        .size:           2
        .value_kind:     hidden_remainder_y
      - .offset:         166
        .size:           2
        .value_kind:     hidden_remainder_z
      - .offset:         184
        .size:           8
        .value_kind:     hidden_global_offset_x
      - .offset:         192
        .size:           8
        .value_kind:     hidden_global_offset_y
      - .offset:         200
        .size:           8
        .value_kind:     hidden_global_offset_z
      - .offset:         208
        .size:           2
        .value_kind:     hidden_grid_dims
      - .offset:         232
        .size:           8
        .value_kind:     hidden_multigrid_sync_arg
      - .offset:         264
        .size:           4
        .value_kind:     hidden_dynamic_lds_size
    .group_segment_fixed_size: 0
    .kernarg_segment_align: 8
    .kernarg_segment_size: 400
    .language:       OpenCL C
    .language_version:
      - 2
      - 0
    .max_flat_workgroup_size: 512
    .name:           _Z10hybrid_fwd6Params
    .private_segment_fixed_size: 0
    .sgpr_count:     108
    .sgpr_spill_count: 107
    .symbol:         _Z10hybrid_fwd6Params.kd
    .uniform_work_group_size: 1
    .uses_dynamic_stack: false
    .vgpr_count:     256
    .vgpr_spill_count: 0
    .wavefront_size: 64
